# P2: FFN2 gate/up weight conversion moved from the post-GEMM tail into the gate/up GEMM's SwiGLU epilogue (one 64x64 item per wave per unit, loads at epilogue start into dead fragment registers, regist
# speedup vs baseline: 1.0019x; 1.0019x over previous
.LBB0_172:
	v_lshrrev_b32_e32 v15, 1, v148
	v_and_b32_e32 v15, 24, v15
	v_and_b32_e32 v14, 15, v148
	v_lshlrev_b32_e32 v16, 1, v15
	v_lshl_or_b32 v150, s1, 6, v14
	v_lshl_or_b32 v14, v14, 6, v16
	v_lshlrev_b32_e32 v16, 2, v148
	s_sext_i32_i16 s36, s0
	s_lshl_b32 s0, s1, 13
	v_and_b32_e32 v16, 32, v16
	v_bitop3_b32 v17, v14, s0, v16 bitop3:0xde
	s_lshl_b32 s0, s4, 5
	s_mov_b64 s[4:5], 0x80
	s_and_b32 s8, s0, 0x60
	s_add_i32 m0, s29, 0x18000
	v_lshl_add_u64 v[6:7], v[6:7], 0, s[4:5]
	s_lshl_b32 s0, s8, 7
	s_waitcnt vmcnt(2)
	s_barrier
	global_load_lds_dwordx4 v[6:7], off
	v_lshl_add_u64 v[4:5], v[4:5], 0, s[4:5]
	s_add_i32 m0, s29, 0x1a000
	s_add_i32 s78, s29, 0x8000
	s_add_i32 s79, s29, 0xa000
	v_bitop3_b32 v151, s0, v14, v16 bitop3:0xf6
	global_load_lds_dwordx4 v[4:5], off
	v_lshl_add_u64 v[0:1], v[0:1], 0, s[4:5]
	s_mov_b32 m0, s78
	s_add_u32 s0, s74, 0x100080
	global_load_lds_dwordx4 v[0:1], off
	v_lshl_add_u64 v[0:1], v[2:3], 0, s[4:5]
	s_mov_b32 m0, s79
	s_addc_u32 s1, s75, 0
	global_load_lds_dwordx4 v[0:1], off
	s_add_i32 m0, s29, 0x1c000
	v_lshl_add_u64 v[0:1], s[0:1], 0, v[130:131]
	global_load_lds_dwordx4 v[0:1], off
	v_lshl_add_u64 v[0:1], s[0:1], 0, v[134:135]
	s_add_i32 m0, s29, 0x1e000
	s_cmpk_lt_u32 s6, 0x100
	global_load_lds_dwordx4 v[0:1], off
	v_lshlrev_b32_e32 v0, 16, v8
	v_and_b32_e32 v0, 0xfffe0000, v0
	v_lshl_add_u32 v0, v9, 13, v0
	v_and_b32_e32 v1, 1, v8
	v_lshl_or_b32 v0, v1, 6, v0
	v_lshl_add_u32 v136, v10, 1, v0
	v_lshlrev_b32_e32 v0, 16, v11
	v_and_b32_e32 v0, 0xfffe0000, v0
	s_waitcnt vmcnt(6)
	v_lshl_add_u32 v0, v12, 13, v0
	v_and_b32_e32 v1, 1, v11
	s_cselect_b64 s[6:7], -1, 0
	v_lshl_or_b32 v0, v1, 6, v0
	s_add_i32 s81, 0, 0x10000
	s_add_i32 s82, 0, 0x14000
	s_ashr_i32 s80, s9, 31
	v_or_b32_e32 v152, s8, v15
	v_mov_b32_e32 v137, v131
	v_lshl_add_u32 v138, v13, 1, v0
	v_mov_b32_e32 v139, v131
	v_mov_b64_e32 v[140:141], 0xb6c
	v_mov_b64_e32 v[142:143], 0xb6b
	v_add_u32_e32 v153, s81, v151
	v_add_u32_e32 v154, s82, v151
	v_add_u32_e32 v155, 0, v17
	s_movk_i32 s83, 0x5600
	s_mov_b32 s8, 0xbfb8aa3b
	v_readlane_b32 s98, v252, 15
	v_readlane_b32 s99, v252, 6
	s_lshl_b32 s98, s98, 3
	s_add_i32 s98, s98, s99
	s_mov_b32 s99, 0

.Lcvs_div_done:
	v_writelane_b32 v255, s99, 9
	v_writelane_b32 v255, s98, 10
	v_readlane_b32 s98, v252, 0
	v_readlane_b32 s99, v252, 1
	s_nop 4
	s_add_u32 s98, s98, 0xffffff08
	s_addc_u32 s99, s99, -1
	s_load_dwordx2 s[100:101], s[98:99], 0xc0
	s_waitcnt lgkmcnt(0)
	v_writelane_b32 v255, s100, 12
	v_writelane_b32 v255, s101, 13
	s_barrier
	s_branch .LBB0_175
.LBB0_173:
	s_mov_b64 s[0:1], 0

.LBB0_185:
	v_readlane_b32 s98, v255, 9
	v_readlane_b32 s99, v255, 10
	v_readlane_b32 s100, v255, 12
	v_readlane_b32 s101, v255, 13
	s_cmp_gt_u32 s98, 63
	s_cbranch_scc1 .Lcve_noissue
	s_mul_i32 s98, s98, 0x560000
	s_lshl_b32 s99, s99, 8
	s_add_u32 s98, s98, s99
	s_add_u32 s100, s100, s98
	s_addc_u32 s101, s101, 0
	v_lshrrev_b32_e32 v232, 4, v148
	v_and_b32_e32 v234, 15, v148
	v_mul_u32_u24_e32 v232, 0xac000, v232
	v_lshl_add_u32 v232, v234, 4, v232
	s_nop 1
	global_load_dwordx4 v[168:171], v232, s[100:101] nt
	s_add_u32 s100, s100, 0x15800
	s_addc_u32 s101, s101, 0
	global_load_dwordx4 v[172:175], v232, s[100:101] nt
	s_add_u32 s100, s100, 0x15800
	s_addc_u32 s101, s101, 0
	global_load_dwordx4 v[176:179], v232, s[100:101] nt
	s_add_u32 s100, s100, 0x15800
	s_addc_u32 s101, s101, 0
	global_load_dwordx4 v[180:183], v232, s[100:101] nt
	s_add_u32 s100, s100, 0x15800
	s_addc_u32 s101, s101, 0
	global_load_dwordx4 v[184:187], v232, s[100:101] nt
	s_add_u32 s100, s100, 0x15800
	s_addc_u32 s101, s101, 0
	global_load_dwordx4 v[188:191], v232, s[100:101] nt
	s_add_u32 s100, s100, 0x15800
	s_addc_u32 s101, s101, 0
	global_load_dwordx4 v[192:195], v232, s[100:101] nt
	s_add_u32 s100, s100, 0x15800
	s_addc_u32 s101, s101, 0
	global_load_dwordx4 v[196:199], v232, s[100:101] nt
	s_add_u32 s100, s100, 0x219800
	s_addc_u32 s101, s101, 0
	global_load_dwordx4 v[200:203], v232, s[100:101] nt
	s_add_u32 s100, s100, 0x15800
	s_addc_u32 s101, s101, 0
	global_load_dwordx4 v[204:207], v232, s[100:101] nt
	s_add_u32 s100, s100, 0x15800
	s_addc_u32 s101, s101, 0
	global_load_dwordx4 v[208:211], v232, s[100:101] nt
	s_add_u32 s100, s100, 0x15800
	s_addc_u32 s101, s101, 0
	global_load_dwordx4 v[212:215], v232, s[100:101] nt
	s_add_u32 s100, s100, 0x15800
	s_addc_u32 s101, s101, 0
	global_load_dwordx4 v[216:219], v232, s[100:101] nt
	s_add_u32 s100, s100, 0x15800
	s_addc_u32 s101, s101, 0
	global_load_dwordx4 v[220:223], v232, s[100:101] nt
	s_add_u32 s100, s100, 0x15800
	s_addc_u32 s101, s101, 0
	global_load_dwordx4 v[224:227], v232, s[100:101] nt
	s_add_u32 s100, s100, 0x15800
	s_addc_u32 s101, s101, 0
	global_load_dwordx4 v[228:231], v232, s[100:101] nt
.Lcve_noissue:
	v_pk_mul_f32 v[158:159], v[126:127], s[8:9] op_sel_hi:[1,0]
	v_pk_mul_f32 v[160:161], v[124:125], s[8:9] op_sel_hi:[1,0]
	v_pk_mul_f32 v[162:163], v[122:123], s[8:9] op_sel_hi:[1,0]
	v_pk_mul_f32 v[164:165], v[120:121], s[8:9] op_sel_hi:[1,0]
	v_exp_f32_e32 v160, v160
	v_exp_f32_e32 v164, v164
	v_exp_f32_e32 v161, v161
	v_exp_f32_e32 v158, v158
	v_exp_f32_e32 v159, v159
	v_exp_f32_e32 v162, v162
	v_exp_f32_e32 v163, v163
	v_exp_f32_e32 v165, v165
	v_pk_add_f32 v[158:159], v[158:159], 1.0 op_sel_hi:[1,0]
	v_pk_add_f32 v[160:161], v[160:161], 1.0 op_sel_hi:[1,0]
	v_pk_add_f32 v[162:163], v[162:163], 1.0 op_sel_hi:[1,0]
	v_pk_add_f32 v[164:165], v[164:165], 1.0 op_sel_hi:[1,0]
	v_rcp_f32_e32 v160, v160
	v_rcp_f32_e32 v164, v164
	v_rcp_f32_e32 v161, v161
	v_rcp_f32_e32 v165, v165
	v_rcp_f32_e32 v158, v158
	v_rcp_f32_e32 v162, v162
	v_rcp_f32_e32 v159, v159
	v_rcp_f32_e32 v163, v163
	v_readlane_b32 s30, v253, 8
	v_lshl_or_b32 v146, s36, 7, v152
	v_readlane_b32 s31, v253, 9
	v_lshl_add_u32 v166, s52, 8, v150
	v_ashrrev_i32_e32 v147, 31, v146
	v_mov_b64_e32 v[144:145], s[30:31]
	v_pk_mul_f32 v[118:119], v[118:119], v[126:127]
	v_pk_mul_f32 v[116:117], v[116:117], v[124:125]
	v_pk_mul_f32 v[114:115], v[114:115], v[122:123]
	v_pk_mul_f32 v[112:113], v[112:113], v[120:121]
	v_mad_i64_i32 v[156:157], s[30:31], v166, s83, v[144:145]
	v_lshlrev_b64 v[146:147], 1, v[146:147]
	v_pk_mul_f32 v[118:119], v[118:119], v[158:159]
	v_pk_mul_f32 v[116:117], v[116:117], v[160:161]
	v_pk_mul_f32 v[120:121], v[114:115], v[162:163]
	v_pk_mul_f32 v[114:115], v[112:113], v[164:165]
	v_lshl_add_u64 v[156:157], v[156:157], 0, v[146:147]
	v_cvt_pk_bf16_f32 v112, v116, v117
	v_cvt_pk_bf16_f32 v113, v118, v119
	v_cvt_pk_bf16_f32 v114, v114, v115
	v_cvt_pk_bf16_f32 v115, v120, v121
	global_store_dwordx4 v[156:157], v[112:115], off
	v_pk_mul_f32 v[116:117], v[108:109], s[8:9] op_sel_hi:[1,0]
	v_pk_mul_f32 v[118:119], v[106:107], s[8:9] op_sel_hi:[1,0]
	v_pk_mul_f32 v[114:115], v[110:111], s[8:9] op_sel_hi:[1,0]
	v_pk_mul_f32 v[120:121], v[104:105], s[8:9] op_sel_hi:[1,0]
	v_exp_f32_e32 v116, v116
	v_exp_f32_e32 v120, v120
	v_exp_f32_e32 v117, v117
	v_exp_f32_e32 v114, v114
	v_exp_f32_e32 v115, v115
	v_exp_f32_e32 v118, v118
	v_exp_f32_e32 v119, v119
	v_exp_f32_e32 v121, v121
	v_pk_add_f32 v[114:115], v[114:115], 1.0 op_sel_hi:[1,0]
	v_pk_add_f32 v[116:117], v[116:117], 1.0 op_sel_hi:[1,0]
	v_pk_add_f32 v[118:119], v[118:119], 1.0 op_sel_hi:[1,0]
	v_pk_add_f32 v[120:121], v[120:121], 1.0 op_sel_hi:[1,0]
	v_rcp_f32_e32 v116, v116
	v_rcp_f32_e32 v120, v120
	v_rcp_f32_e32 v117, v117
	v_rcp_f32_e32 v121, v121
	v_rcp_f32_e32 v114, v114
	v_rcp_f32_e32 v118, v118
	v_rcp_f32_e32 v115, v115
	v_rcp_f32_e32 v119, v119
	v_or_b32_e32 v112, 16, v166
	v_pk_mul_f32 v[102:103], v[102:103], v[110:111]
	v_pk_mul_f32 v[100:101], v[100:101], v[108:109]
	v_pk_mul_f32 v[98:99], v[98:99], v[106:107]
	v_pk_mul_f32 v[96:97], v[96:97], v[104:105]
	v_mad_i64_i32 v[112:113], s[30:31], v112, s83, v[144:145]
	v_pk_mul_f32 v[102:103], v[102:103], v[114:115]
	v_pk_mul_f32 v[100:101], v[100:101], v[116:117]
	v_pk_mul_f32 v[104:105], v[98:99], v[118:119]
	v_pk_mul_f32 v[98:99], v[96:97], v[120:121]
	v_lshl_add_u64 v[112:113], v[112:113], 0, v[146:147]
	v_cvt_pk_bf16_f32 v96, v100, v101
	v_cvt_pk_bf16_f32 v97, v102, v103
	v_cvt_pk_bf16_f32 v98, v98, v99
	v_cvt_pk_bf16_f32 v99, v104, v105
	global_store_dwordx4 v[112:113], v[96:99], off
	v_pk_mul_f32 v[100:101], v[92:93], s[8:9] op_sel_hi:[1,0]
	v_pk_mul_f32 v[102:103], v[90:91], s[8:9] op_sel_hi:[1,0]
	v_pk_mul_f32 v[98:99], v[94:95], s[8:9] op_sel_hi:[1,0]
	v_pk_mul_f32 v[104:105], v[88:89], s[8:9] op_sel_hi:[1,0]
	v_exp_f32_e32 v100, v100
	v_exp_f32_e32 v104, v104
	v_exp_f32_e32 v101, v101
	v_exp_f32_e32 v98, v98
	v_exp_f32_e32 v99, v99
	v_exp_f32_e32 v102, v102
	v_exp_f32_e32 v103, v103
	v_exp_f32_e32 v105, v105
	v_pk_add_f32 v[98:99], v[98:99], 1.0 op_sel_hi:[1,0]
	v_pk_add_f32 v[100:101], v[100:101], 1.0 op_sel_hi:[1,0]
	v_pk_add_f32 v[102:103], v[102:103], 1.0 op_sel_hi:[1,0]
	v_pk_add_f32 v[104:105], v[104:105], 1.0 op_sel_hi:[1,0]
	v_rcp_f32_e32 v100, v100
	v_rcp_f32_e32 v104, v104
	v_rcp_f32_e32 v101, v101
	v_rcp_f32_e32 v105, v105
	v_rcp_f32_e32 v98, v98
	v_rcp_f32_e32 v102, v102
	v_rcp_f32_e32 v99, v99
	v_rcp_f32_e32 v103, v103
	v_or_b32_e32 v96, 32, v166
	v_pk_mul_f32 v[86:87], v[86:87], v[94:95]
	v_pk_mul_f32 v[84:85], v[84:85], v[92:93]
	v_pk_mul_f32 v[82:83], v[82:83], v[90:91]
	v_pk_mul_f32 v[80:81], v[80:81], v[88:89]
	v_mad_i64_i32 v[96:97], s[30:31], v96, s83, v[144:145]
	v_pk_mul_f32 v[86:87], v[86:87], v[98:99]
	v_pk_mul_f32 v[84:85], v[84:85], v[100:101]
	v_pk_mul_f32 v[88:89], v[82:83], v[102:103]
	v_pk_mul_f32 v[82:83], v[80:81], v[104:105]
	v_lshl_add_u64 v[96:97], v[96:97], 0, v[146:147]
	v_cvt_pk_bf16_f32 v80, v84, v85
	v_cvt_pk_bf16_f32 v81, v86, v87
	v_cvt_pk_bf16_f32 v82, v82, v83
	v_cvt_pk_bf16_f32 v83, v88, v89
	global_store_dwordx4 v[96:97], v[80:83], off
	v_pk_mul_f32 v[84:85], v[76:77], s[8:9] op_sel_hi:[1,0]
	v_pk_mul_f32 v[86:87], v[74:75], s[8:9] op_sel_hi:[1,0]
	v_pk_mul_f32 v[82:83], v[78:79], s[8:9] op_sel_hi:[1,0]
	v_pk_mul_f32 v[88:89], v[72:73], s[8:9] op_sel_hi:[1,0]
	v_exp_f32_e32 v84, v84
	v_exp_f32_e32 v88, v88
	v_exp_f32_e32 v85, v85
	v_exp_f32_e32 v82, v82
	v_exp_f32_e32 v83, v83
	v_exp_f32_e32 v86, v86
	v_exp_f32_e32 v87, v87
	v_exp_f32_e32 v89, v89
	v_pk_add_f32 v[82:83], v[82:83], 1.0 op_sel_hi:[1,0]
	v_pk_add_f32 v[84:85], v[84:85], 1.0 op_sel_hi:[1,0]
	v_pk_add_f32 v[86:87], v[86:87], 1.0 op_sel_hi:[1,0]
	v_pk_add_f32 v[88:89], v[88:89], 1.0 op_sel_hi:[1,0]
	v_rcp_f32_e32 v84, v84
	v_rcp_f32_e32 v88, v88
	v_rcp_f32_e32 v85, v85
	v_rcp_f32_e32 v89, v89
	v_rcp_f32_e32 v82, v82
	v_rcp_f32_e32 v86, v86
	v_rcp_f32_e32 v83, v83
	v_rcp_f32_e32 v87, v87
	v_or_b32_e32 v80, 48, v166
	v_pk_mul_f32 v[70:71], v[70:71], v[78:79]
	v_pk_mul_f32 v[68:69], v[68:69], v[76:77]
	v_pk_mul_f32 v[66:67], v[66:67], v[74:75]
	v_pk_mul_f32 v[64:65], v[64:65], v[72:73]
	v_mad_i64_i32 v[80:81], s[30:31], v80, s83, v[144:145]
	v_pk_mul_f32 v[70:71], v[70:71], v[82:83]
	v_pk_mul_f32 v[68:69], v[68:69], v[84:85]
	v_pk_mul_f32 v[72:73], v[66:67], v[86:87]
	v_pk_mul_f32 v[66:67], v[64:65], v[88:89]
	v_lshl_add_u64 v[80:81], v[80:81], 0, v[146:147]
	v_cvt_pk_bf16_f32 v64, v68, v69
	v_cvt_pk_bf16_f32 v65, v70, v71
	v_cvt_pk_bf16_f32 v66, v66, v67
	v_cvt_pk_bf16_f32 v67, v72, v73
	global_store_dwordx4 v[80:81], v[64:67], off
	v_pk_mul_f32 v[68:69], v[60:61], s[8:9] op_sel_hi:[1,0]
	v_pk_mul_f32 v[70:71], v[58:59], s[8:9] op_sel_hi:[1,0]
	v_pk_mul_f32 v[66:67], v[62:63], s[8:9] op_sel_hi:[1,0]
	v_pk_mul_f32 v[72:73], v[56:57], s[8:9] op_sel_hi:[1,0]
	v_exp_f32_e32 v68, v68
	v_exp_f32_e32 v72, v72
	v_exp_f32_e32 v69, v69
	v_exp_f32_e32 v66, v66
	v_exp_f32_e32 v67, v67
	v_exp_f32_e32 v70, v70
	v_exp_f32_e32 v71, v71
	v_exp_f32_e32 v73, v73
	v_pk_add_f32 v[66:67], v[66:67], 1.0 op_sel_hi:[1,0]
	v_pk_add_f32 v[68:69], v[68:69], 1.0 op_sel_hi:[1,0]
	v_pk_add_f32 v[70:71], v[70:71], 1.0 op_sel_hi:[1,0]
	v_pk_add_f32 v[72:73], v[72:73], 1.0 op_sel_hi:[1,0]
	v_rcp_f32_e32 v68, v68
	v_rcp_f32_e32 v72, v72
	v_rcp_f32_e32 v69, v69
	v_rcp_f32_e32 v73, v73
	v_rcp_f32_e32 v66, v66
	v_rcp_f32_e32 v70, v70
	v_rcp_f32_e32 v67, v67
	v_rcp_f32_e32 v71, v71
	v_add_u32_e32 v64, 0x80, v166
	v_pk_mul_f32 v[54:55], v[54:55], v[62:63]
	v_pk_mul_f32 v[52:53], v[52:53], v[60:61]
	v_pk_mul_f32 v[50:51], v[50:51], v[58:59]
	v_pk_mul_f32 v[48:49], v[48:49], v[56:57]
	v_mad_i64_i32 v[64:65], s[30:31], v64, s83, v[144:145]
	v_pk_mul_f32 v[54:55], v[54:55], v[66:67]
	v_pk_mul_f32 v[52:53], v[52:53], v[68:69]
	v_pk_mul_f32 v[56:57], v[50:51], v[70:71]
	v_pk_mul_f32 v[50:51], v[48:49], v[72:73]
	v_lshl_add_u64 v[64:65], v[64:65], 0, v[146:147]
	v_cvt_pk_bf16_f32 v48, v52, v53
	v_cvt_pk_bf16_f32 v49, v54, v55
	v_cvt_pk_bf16_f32 v50, v50, v51
	v_cvt_pk_bf16_f32 v51, v56, v57
	global_store_dwordx4 v[64:65], v[48:51], off
	v_pk_mul_f32 v[52:53], v[44:45], s[8:9] op_sel_hi:[1,0]
	v_pk_mul_f32 v[54:55], v[42:43], s[8:9] op_sel_hi:[1,0]
	v_pk_mul_f32 v[50:51], v[46:47], s[8:9] op_sel_hi:[1,0]
	v_pk_mul_f32 v[56:57], v[40:41], s[8:9] op_sel_hi:[1,0]
	v_exp_f32_e32 v52, v52
	v_exp_f32_e32 v56, v56
	v_exp_f32_e32 v53, v53
	v_exp_f32_e32 v50, v50
	v_exp_f32_e32 v51, v51
	v_exp_f32_e32 v54, v54
	v_exp_f32_e32 v55, v55
	v_exp_f32_e32 v57, v57
	v_pk_add_f32 v[50:51], v[50:51], 1.0 op_sel_hi:[1,0]
	v_pk_add_f32 v[52:53], v[52:53], 1.0 op_sel_hi:[1,0]
	v_pk_add_f32 v[54:55], v[54:55], 1.0 op_sel_hi:[1,0]
	v_pk_add_f32 v[56:57], v[56:57], 1.0 op_sel_hi:[1,0]
	v_rcp_f32_e32 v52, v52
	v_rcp_f32_e32 v56, v56
	v_rcp_f32_e32 v53, v53
	v_rcp_f32_e32 v57, v57
	v_rcp_f32_e32 v50, v50
	v_rcp_f32_e32 v54, v54
	v_rcp_f32_e32 v51, v51
	v_rcp_f32_e32 v55, v55
	v_add_u32_e32 v48, 0x90, v166
	v_pk_mul_f32 v[38:39], v[38:39], v[46:47]
	v_pk_mul_f32 v[36:37], v[36:37], v[44:45]
	v_pk_mul_f32 v[34:35], v[34:35], v[42:43]
	v_pk_mul_f32 v[32:33], v[32:33], v[40:41]
	v_mad_i64_i32 v[48:49], s[30:31], v48, s83, v[144:145]
	v_pk_mul_f32 v[38:39], v[38:39], v[50:51]
	v_pk_mul_f32 v[36:37], v[36:37], v[52:53]
	v_pk_mul_f32 v[40:41], v[34:35], v[54:55]
	v_pk_mul_f32 v[34:35], v[32:33], v[56:57]
	v_lshl_add_u64 v[48:49], v[48:49], 0, v[146:147]
	v_cvt_pk_bf16_f32 v32, v36, v37
	v_cvt_pk_bf16_f32 v33, v38, v39
	v_cvt_pk_bf16_f32 v34, v34, v35
	v_cvt_pk_bf16_f32 v35, v40, v41
	global_store_dwordx4 v[48:49], v[32:35], off
	v_pk_mul_f32 v[36:37], v[28:29], s[8:9] op_sel_hi:[1,0]
	v_pk_mul_f32 v[38:39], v[26:27], s[8:9] op_sel_hi:[1,0]
	v_pk_mul_f32 v[34:35], v[30:31], s[8:9] op_sel_hi:[1,0]
	v_pk_mul_f32 v[40:41], v[24:25], s[8:9] op_sel_hi:[1,0]
	v_exp_f32_e32 v36, v36
	v_exp_f32_e32 v40, v40
	v_exp_f32_e32 v37, v37
	v_exp_f32_e32 v34, v34
	v_exp_f32_e32 v35, v35
	v_exp_f32_e32 v38, v38
	v_exp_f32_e32 v39, v39
	v_exp_f32_e32 v41, v41
	v_pk_add_f32 v[34:35], v[34:35], 1.0 op_sel_hi:[1,0]
	v_pk_add_f32 v[36:37], v[36:37], 1.0 op_sel_hi:[1,0]
	v_pk_add_f32 v[38:39], v[38:39], 1.0 op_sel_hi:[1,0]
	v_pk_add_f32 v[40:41], v[40:41], 1.0 op_sel_hi:[1,0]
	v_rcp_f32_e32 v36, v36
	v_rcp_f32_e32 v40, v40
	v_rcp_f32_e32 v37, v37
	v_rcp_f32_e32 v41, v41
	v_rcp_f32_e32 v34, v34
	v_rcp_f32_e32 v38, v38
	v_rcp_f32_e32 v35, v35
	v_rcp_f32_e32 v39, v39
	v_add_u32_e32 v32, 0xa0, v166
	v_pk_mul_f32 v[22:23], v[22:23], v[30:31]
	v_pk_mul_f32 v[20:21], v[20:21], v[28:29]
	v_pk_mul_f32 v[18:19], v[18:19], v[26:27]
	v_pk_mul_f32 v[16:17], v[16:17], v[24:25]
	v_mad_i64_i32 v[32:33], s[30:31], v32, s83, v[144:145]
	v_pk_mul_f32 v[22:23], v[22:23], v[34:35]
	v_pk_mul_f32 v[20:21], v[20:21], v[36:37]
	v_pk_mul_f32 v[24:25], v[18:19], v[38:39]
	v_pk_mul_f32 v[18:19], v[16:17], v[40:41]
	v_lshl_add_u64 v[32:33], v[32:33], 0, v[146:147]
	v_cvt_pk_bf16_f32 v16, v20, v21
	v_cvt_pk_bf16_f32 v17, v22, v23
	v_cvt_pk_bf16_f32 v18, v18, v19
	v_cvt_pk_bf16_f32 v19, v24, v25
	global_store_dwordx4 v[32:33], v[16:19], off
	v_pk_mul_f32 v[20:21], v[12:13], s[8:9] op_sel_hi:[1,0]
	v_pk_mul_f32 v[22:23], v[10:11], s[8:9] op_sel_hi:[1,0]
	v_pk_mul_f32 v[18:19], v[14:15], s[8:9] op_sel_hi:[1,0]
	v_pk_mul_f32 v[24:25], v[8:9], s[8:9] op_sel_hi:[1,0]
	v_exp_f32_e32 v20, v20
	v_exp_f32_e32 v24, v24
	v_exp_f32_e32 v21, v21
	v_exp_f32_e32 v18, v18
	v_exp_f32_e32 v19, v19
	v_exp_f32_e32 v22, v22
	v_exp_f32_e32 v23, v23
	v_exp_f32_e32 v25, v25
	v_pk_add_f32 v[18:19], v[18:19], 1.0 op_sel_hi:[1,0]
	v_pk_add_f32 v[20:21], v[20:21], 1.0 op_sel_hi:[1,0]
	v_pk_add_f32 v[22:23], v[22:23], 1.0 op_sel_hi:[1,0]
	v_pk_add_f32 v[24:25], v[24:25], 1.0 op_sel_hi:[1,0]
	v_rcp_f32_e32 v20, v20
	v_rcp_f32_e32 v24, v24
	v_rcp_f32_e32 v21, v21
	v_rcp_f32_e32 v25, v25
	v_rcp_f32_e32 v18, v18
	v_rcp_f32_e32 v22, v22
	v_rcp_f32_e32 v19, v19
	v_rcp_f32_e32 v23, v23
	v_add_u32_e32 v16, 0xb0, v166
	v_pk_mul_f32 v[6:7], v[6:7], v[14:15]
	v_pk_mul_f32 v[4:5], v[4:5], v[12:13]
	v_pk_mul_f32 v[2:3], v[2:3], v[10:11]
	v_pk_mul_f32 v[0:1], v[0:1], v[8:9]
	v_mad_i64_i32 v[16:17], s[30:31], v16, s83, v[144:145]
	v_pk_mul_f32 v[6:7], v[6:7], v[18:19]
	v_pk_mul_f32 v[4:5], v[4:5], v[20:21]
	v_pk_mul_f32 v[8:9], v[2:3], v[22:23]
	v_pk_mul_f32 v[2:3], v[0:1], v[24:25]
	v_lshl_add_u64 v[16:17], v[16:17], 0, v[146:147]
	v_cvt_pk_bf16_f32 v0, v4, v5
	v_cvt_pk_bf16_f32 v1, v6, v7
	v_cvt_pk_bf16_f32 v2, v2, v3
	v_cvt_pk_bf16_f32 v3, v8, v9
	s_andn2_b64 vcc, exec, s[0:1]
	s_mov_b64 s[0:1], -1
	global_store_dwordx4 v[16:17], v[0:3], off
	v_readlane_b32 s98, v255, 9
	v_readlane_b32 s99, v255, 10
	s_cmp_gt_u32 s98, 63
	s_cbranch_scc1 .Lcve_nocons
	s_cmpk_ge_u32 s99, 0xac
	s_cselect_b32 s100, 0xac, 0
	s_cselect_b32 s101, 0x80, 0
	s_sub_i32 s100, s99, s100
	s_lshr_b32 s99, s100, 1
	s_lshl_b32 s99, s99, 8
	s_and_b32 s100, s100, 1
	s_lshl_b32 s100, s100, 6
	s_add_i32 s99, s99, s101
	s_add_i32 s99, s99, s100
	s_lshl_b32 s99, s99, 13
	s_lshl_b32 s98, s98, 7
	s_add_u32 s99, s99, s98
	s_add_u32 s99, s99, 0x10a00000
	s_add_u32 s100, s90, s99
	s_addc_u32 s101, s91, 0
	v_and_b32_e32 v233, 15, v148
	v_lshrrev_b32_e32 v234, 4, v148
	v_lshlrev_b32_e32 v233, 15, v233
	v_lshl_add_u32 v233, v234, 4, v233
	s_waitcnt vmcnt(8)
	v_cvt_pk_bf16_f32 v248, v168, v172
	v_cvt_pk_bf16_f32 v249, v176, v180
	v_cvt_pk_bf16_f32 v250, v184, v188
	v_cvt_pk_bf16_f32 v251, v192, v196
	global_store_dwordx4 v233, v[248:251], s[100:101]
	s_nop 1
	v_cvt_pk_bf16_f32 v248, v200, v204
	v_cvt_pk_bf16_f32 v249, v208, v212
	v_cvt_pk_bf16_f32 v250, v216, v220
	v_cvt_pk_bf16_f32 v251, v224, v228
	global_store_dwordx4 v233, v[248:251], s[100:101] offset:64
	s_nop 1
	s_add_u32 s100, s100, 0x2000
	s_addc_u32 s101, s101, 0
	v_cvt_pk_bf16_f32 v248, v169, v173
	v_cvt_pk_bf16_f32 v249, v177, v181
	v_cvt_pk_bf16_f32 v250, v185, v189
	v_cvt_pk_bf16_f32 v251, v193, v197
	global_store_dwordx4 v233, v[248:251], s[100:101]
	s_nop 1
	v_cvt_pk_bf16_f32 v248, v201, v205
	v_cvt_pk_bf16_f32 v249, v209, v213
	v_cvt_pk_bf16_f32 v250, v217, v221
	v_cvt_pk_bf16_f32 v251, v225, v229
	global_store_dwordx4 v233, v[248:251], s[100:101] offset:64
	s_nop 1
	s_add_u32 s100, s100, 0x2000
	s_addc_u32 s101, s101, 0
	v_cvt_pk_bf16_f32 v248, v170, v174
	v_cvt_pk_bf16_f32 v249, v178, v182
	v_cvt_pk_bf16_f32 v250, v186, v190
	v_cvt_pk_bf16_f32 v251, v194, v198
	global_store_dwordx4 v233, v[248:251], s[100:101]
	s_nop 1
	v_cvt_pk_bf16_f32 v248, v202, v206
	v_cvt_pk_bf16_f32 v249, v210, v214
	v_cvt_pk_bf16_f32 v250, v218, v222
	v_cvt_pk_bf16_f32 v251, v226, v230
	global_store_dwordx4 v233, v[248:251], s[100:101] offset:64
	s_nop 1
	s_add_u32 s100, s100, 0x2000
	s_addc_u32 s101, s101, 0
	v_cvt_pk_bf16_f32 v248, v171, v175
	v_cvt_pk_bf16_f32 v249, v179, v183
	v_cvt_pk_bf16_f32 v250, v187, v191
	v_cvt_pk_bf16_f32 v251, v195, v199
	global_store_dwordx4 v233, v[248:251], s[100:101]
	s_nop 1
	v_cvt_pk_bf16_f32 v248, v203, v207
	v_cvt_pk_bf16_f32 v249, v211, v215
	v_cvt_pk_bf16_f32 v250, v219, v223
	v_cvt_pk_bf16_f32 v251, v227, v231
	global_store_dwordx4 v233, v[248:251], s[100:101] offset:64
	s_nop 1
	v_readlane_b32 s98, v255, 9
	v_readlane_b32 s99, v255, 10
	s_add_i32 s98, s98, 5
	s_addk_i32 s99, 0xe8
	s_cmpk_ge_u32 s99, 0x158
	s_cselect_b32 s100, 0x158, 0
	s_cselect_b32 s101, 1, 0
	s_sub_i32 s99, s99, s100
	s_add_i32 s98, s98, s101
	v_writelane_b32 v255, s98, 9
	v_writelane_b32 v255, s99, 10
.Lcve_nocons:
	s_cbranch_vccnz .LBB0_174
	s_andn2_b64 vcc, exec, s[2:3]
	s_cbranch_vccnz .LBB0_173
	s_barrier
	s_branch .LBB0_173
